# grid barrier made XCD-hierarchical: per-XCD arrival counters, one L2 write-back per XCD by its last arriver, global leader counter polled by all
# speedup vs baseline: 1.0346x; 1.0175x over previous
; #define SEAM(k) do { if (IN(k) && IN((k) + 1)) grid.sync(); if (PROBE_PH >= 0) { const unsigned long long tn_ = __builtin_amdgcn_s_memrealtime(); if ((PROBE_PH >> (k)) & 1) tp1 += tn_ - tp0; tp0 = tn_; } } while (0)
; __global__ void __launch_bounds__(512, 2) mega(Params p) {
;     ...
;     cg::grid_group grid = cg::this_grid();
;     const int lo = p.ph_lo, hi = p.ph_hi;
;     ...
;     SEAM(0);
.LBB0_25:
	s_cmp_gt_i32 s67, 1
	s_cselect_b64 s[2:3], -1, 0
	s_and_b64 s[0:1], s[0:1], s[2:3]
	s_andn2_b64 vcc, exec, s[0:1]
	s_cbranch_vccnz .LBB0_37
	v_and_b32_e32 v1, 0x3fffffff, v0
	v_cmp_eq_u32_e32 vcc, 0, v1
	s_waitcnt lgkmcnt(0)
	s_barrier
	s_and_saveexec_b64 s[0:1], vcc
	s_cbranch_execz .LBB0_36
	buffer_wbl2 sc1
	s_waitcnt vmcnt(0)
	s_load_dwordx2 s[4:5], s[68:69], 0x58
	v_mov_b32_e32 v3, 0
	s_mov_b64 s[6:7], exec
	v_mbcnt_lo_u32_b32 v2, s6, 0
	v_mbcnt_hi_u32_b32 v2, s7, v2
	s_waitcnt lgkmcnt(0)
	s_cmp_lg_u32 s70, 0
	s_cbranch_scc1 .Lfs_boot_skip
	global_store_dword v3, v3, s[4:5] offset:16 sc0 sc1
	global_store_dword v3, v3, s[4:5] offset:20 sc0 sc1
	global_store_dword v3, v3, s[4:5] offset:24 sc0 sc1
	global_store_dword v3, v3, s[4:5] offset:28 sc0 sc1
	global_store_dword v3, v3, s[4:5] offset:36 sc0 sc1
	s_waitcnt vmcnt(0)

; #define SEAM(k) do { if (IN(k) && IN((k) + 1)) grid.sync(); if (PROBE_PH >= 0) { const unsigned long long tn_ = __builtin_amdgcn_s_memrealtime(); if ((PROBE_PH >> (k)) & 1) tp1 += tn_ - tp0; tp0 = tn_; } } while (0)
; __global__ void __launch_bounds__(512, 2) mega(Params p) {
;     ...
;     SEAM(1);
.LBB0_284:
	s_cmp_gt_i32 s67, 2
	s_cselect_b64 s[2:3], -1, 0
	s_and_b64 s[0:1], s[0:1], s[2:3]
	s_andn2_b64 vcc, exec, s[0:1]
	s_cbranch_vccnz .LBB0_296
	v_and_b32_e32 v1, 0x3fffffff, v0
	v_cmp_eq_u32_e32 vcc, 0, v1
	s_waitcnt vmcnt(0) lgkmcnt(0)
	s_barrier
	s_and_saveexec_b64 s[0:1], vcc
	s_cbranch_execz .LBB0_295
	s_load_dwordx2 s[4:5], s[68:69], 0x58
	s_getreg_b32 s101, hwreg(HW_REG_XCC_ID)
	s_add_u32 s100, s100, 1
	s_and_b32 s101, s101, 7
	s_lshr_b32 s98, s101, 1
	s_lshl_b32 s98, s98, 2
	s_and_b32 s99, s101, 1
	s_lshl_b32 s99, s99, 4
	v_mov_b32_e32 v3, s98
	v_mov_b32_e32 v1, 1
	v_lshlrev_b32_e32 v1, s99, v1
	s_waitcnt vmcnt(0) lgkmcnt(0)
	global_atomic_add v2, v3, v1, s[4:5] offset:16 sc0
	s_load_dword s101, s[4:5], 0x28
	s_waitcnt vmcnt(0)
	v_lshrrev_b32_e32 v2, s99, v2
	v_and_b32_e32 v2, 0xffff, v2
	v_add_u32_e32 v2, 1, v2
	s_lshl_b32 s98, s100, 5
	v_mov_b32_e32 v3, 0
	v_mov_b32_e32 v1, 1
	v_cmp_eq_u32_e32 vcc, s98, v2
	s_waitcnt lgkmcnt(0)
	s_lshr_b32 s101, s101, 5
	s_mul_i32 s99, s100, s101
	s_and_saveexec_b64 s[6:7], vcc
	s_cbranch_execz .Lhs_nl_1
	buffer_wbl2 sc1
	s_waitcnt vmcnt(0)
	global_atomic_add v3, v1, s[4:5] offset:36
.Lhs_nl_1:
	s_mov_b64 exec, s[6:7]
	s_mov_b64 s[6:7], 0
.Lhs_poll_1:
	global_load_dword v2, v3, s[4:5] offset:36 sc1
	s_waitcnt vmcnt(0)
	v_subrev_u32_e32 v2, s99, v2
	v_cmp_le_i32_e32 vcc, 0, v2
	s_or_b64 s[6:7], vcc, s[6:7]
	s_andn2_b64 exec, exec, s[6:7]
	s_cbranch_execz .Lhs_done_1
	s_sleep 2
	s_branch .Lhs_poll_1

; #define SEAM(k) do { if (IN(k) && IN((k) + 1)) grid.sync(); if (PROBE_PH >= 0) { const unsigned long long tn_ = __builtin_amdgcn_s_memrealtime(); if ((PROBE_PH >> (k)) & 1) tp1 += tn_ - tp0; tp0 = tn_; } } while (0)
; __global__ void __launch_bounds__(512, 2) mega(Params p) {
;     ...
;     SEAM(2);
.LBB0_359:
	s_cmp_gt_i32 s67, 3
	s_cselect_b64 s[0:1], -1, 0
	s_and_b64 s[2:3], s[8:9], s[0:1]
	s_andn2_b64 vcc, exec, s[2:3]
	s_cbranch_vccnz .LBB0_371
	v_and_b32_e32 v1, 0x3fffffff, v0
	v_cmp_eq_u32_e32 vcc, 0, v1
	s_waitcnt vmcnt(0) lgkmcnt(0)
	s_barrier
	s_and_saveexec_b64 s[2:3], vcc
	s_cbranch_execz .LBB0_370
	s_load_dwordx2 s[4:5], s[68:69], 0x58
	s_getreg_b32 s101, hwreg(HW_REG_XCC_ID)
	s_add_u32 s100, s100, 1
	s_and_b32 s101, s101, 7
	s_lshr_b32 s98, s101, 1
	s_lshl_b32 s98, s98, 2
	s_and_b32 s99, s101, 1
	s_lshl_b32 s99, s99, 4
	v_mov_b32_e32 v3, s98
	v_mov_b32_e32 v1, 1
	v_lshlrev_b32_e32 v1, s99, v1
	s_waitcnt vmcnt(0) lgkmcnt(0)
	global_atomic_add v2, v3, v1, s[4:5] offset:16 sc0
	s_load_dword s101, s[4:5], 0x28
	s_waitcnt vmcnt(0)
	v_lshrrev_b32_e32 v2, s99, v2
	v_and_b32_e32 v2, 0xffff, v2
	v_add_u32_e32 v2, 1, v2
	s_lshl_b32 s98, s100, 5
	v_mov_b32_e32 v3, 0
	v_mov_b32_e32 v1, 1
	v_cmp_eq_u32_e32 vcc, s98, v2
	s_waitcnt lgkmcnt(0)
	s_lshr_b32 s101, s101, 5
	s_mul_i32 s99, s100, s101
	s_and_saveexec_b64 s[6:7], vcc
	s_cbranch_execz .Lhs_nl_2
	buffer_wbl2 sc1
	s_waitcnt vmcnt(0)
	global_atomic_add v3, v1, s[4:5] offset:36

; #define SEAM(k) do { if (IN(k) && IN((k) + 1)) grid.sync(); if (PROBE_PH >= 0) { const unsigned long long tn_ = __builtin_amdgcn_s_memrealtime(); if ((PROBE_PH >> (k)) & 1) tp1 += tn_ - tp0; tp0 = tn_; } } while (0)
; __global__ void __launch_bounds__(512, 2) mega(Params p) {
;     ...
;     SEAM(3);
.LBB0_399:
	s_cmp_gt_i32 s67, 4
	s_cselect_b64 s[2:3], -1, 0
	s_and_b64 s[0:1], s[0:1], s[2:3]
	s_andn2_b64 vcc, exec, s[0:1]
	s_cbranch_vccnz .LBB0_411
	v_and_b32_e32 v1, 0x3fffffff, v0
	v_cmp_eq_u32_e32 vcc, 0, v1
	s_waitcnt vmcnt(0) lgkmcnt(0)
	s_barrier
	s_and_saveexec_b64 s[0:1], vcc
	s_cbranch_execz .LBB0_410
	s_load_dwordx2 s[4:5], s[68:69], 0x58
	s_getreg_b32 s101, hwreg(HW_REG_XCC_ID)
	s_add_u32 s100, s100, 1
	s_and_b32 s101, s101, 7
	s_lshr_b32 s98, s101, 1
	s_lshl_b32 s98, s98, 2
	s_and_b32 s99, s101, 1
	s_lshl_b32 s99, s99, 4
	v_mov_b32_e32 v3, s98
	v_mov_b32_e32 v1, 1
	v_lshlrev_b32_e32 v1, s99, v1
	s_waitcnt vmcnt(0) lgkmcnt(0)
	global_atomic_add v2, v3, v1, s[4:5] offset:16 sc0
	s_load_dword s101, s[4:5], 0x28
	s_waitcnt vmcnt(0)
	v_lshrrev_b32_e32 v2, s99, v2
	v_and_b32_e32 v2, 0xffff, v2
	v_add_u32_e32 v2, 1, v2
	s_lshl_b32 s98, s100, 5
	v_mov_b32_e32 v3, 0
	v_mov_b32_e32 v1, 1
	v_cmp_eq_u32_e32 vcc, s98, v2
	s_waitcnt lgkmcnt(0)
	s_lshr_b32 s101, s101, 5
	s_mul_i32 s99, s100, s101
	s_and_saveexec_b64 s[6:7], vcc
	s_cbranch_execz .Lhs_nl_3
	buffer_wbl2 sc1
	s_waitcnt vmcnt(0)
	global_atomic_add v3, v1, s[4:5] offset:36

; #define SEAM(k) do { if (IN(k) && IN((k) + 1)) grid.sync(); if (PROBE_PH >= 0) { const unsigned long long tn_ = __builtin_amdgcn_s_memrealtime(); if ((PROBE_PH >> (k)) & 1) tp1 += tn_ - tp0; tp0 = tn_; } } while (0)
; __global__ void __launch_bounds__(512, 2) mega(Params p) {
;     ...
;     SEAM(4);
.LBB0_578:
	s_cmp_gt_i32 s67, 5
	v_readlane_b32 s2, v251, 34
	s_cselect_b64 s[0:1], -1, 0
	v_readlane_b32 s3, v251, 35
	s_and_b64 s[2:3], s[2:3], s[0:1]
	s_andn2_b64 vcc, exec, s[2:3]
	s_cbranch_vccnz .LBB0_590
	v_and_b32_e32 v1, 0x3fffffff, v0
	v_cmp_eq_u32_e32 vcc, 0, v1
	s_waitcnt vmcnt(0) lgkmcnt(0)
	s_barrier
	s_and_saveexec_b64 s[2:3], vcc
	s_cbranch_execz .LBB0_589
	s_load_dwordx2 s[4:5], s[68:69], 0x58
	s_getreg_b32 s101, hwreg(HW_REG_XCC_ID)
	s_add_u32 s100, s100, 1
	s_and_b32 s101, s101, 7
	s_lshr_b32 s98, s101, 1
	s_lshl_b32 s98, s98, 2
	s_and_b32 s99, s101, 1
	s_lshl_b32 s99, s99, 4
	v_mov_b32_e32 v3, s98
	v_mov_b32_e32 v1, 1
	v_lshlrev_b32_e32 v1, s99, v1
	s_waitcnt vmcnt(0) lgkmcnt(0)
	global_atomic_add v2, v3, v1, s[4:5] offset:16 sc0
	s_load_dword s101, s[4:5], 0x28
	s_waitcnt vmcnt(0)
	v_lshrrev_b32_e32 v2, s99, v2
	v_and_b32_e32 v2, 0xffff, v2
	v_add_u32_e32 v2, 1, v2
	s_lshl_b32 s98, s100, 5
	v_mov_b32_e32 v3, 0
	v_mov_b32_e32 v1, 1
	v_cmp_eq_u32_e32 vcc, s98, v2
	s_waitcnt lgkmcnt(0)
	s_lshr_b32 s101, s101, 5
	s_mul_i32 s99, s100, s101
	s_and_saveexec_b64 s[6:7], vcc
	s_cbranch_execz .Lhs_nl_4
	buffer_wbl2 sc1
	s_waitcnt vmcnt(0)
	global_atomic_add v3, v1, s[4:5] offset:36

; #define SEAM(k) do { if (IN(k) && IN((k) + 1)) grid.sync(); if (PROBE_PH >= 0) { const unsigned long long tn_ = __builtin_amdgcn_s_memrealtime(); if ((PROBE_PH >> (k)) & 1) tp1 += tn_ - tp0; tp0 = tn_; } } while (0)
; __global__ void __launch_bounds__(512, 2) mega(Params p) {
;     ...
;     SEAM(5);
.LBB0_625:
	s_cmp_gt_i32 s67, 6
	s_cselect_b64 s[2:3], -1, 0
	s_and_b64 s[0:1], s[0:1], s[2:3]
	s_andn2_b64 vcc, exec, s[0:1]
	s_cbranch_vccnz .LBB0_637
	v_and_b32_e32 v1, 0x3fffffff, v0
	v_cmp_eq_u32_e32 vcc, 0, v1
	s_waitcnt vmcnt(0) lgkmcnt(0)
	s_barrier
	s_and_saveexec_b64 s[0:1], vcc
	s_cbranch_execz .LBB0_636
	s_load_dwordx2 s[4:5], s[68:69], 0x58
	s_getreg_b32 s101, hwreg(HW_REG_XCC_ID)
	s_add_u32 s100, s100, 1
	s_and_b32 s101, s101, 7
	s_lshr_b32 s98, s101, 1
	s_lshl_b32 s98, s98, 2
	s_and_b32 s99, s101, 1
	s_lshl_b32 s99, s99, 4
	v_mov_b32_e32 v3, s98
	v_mov_b32_e32 v1, 1
	v_lshlrev_b32_e32 v1, s99, v1
	s_waitcnt vmcnt(0) lgkmcnt(0)
	global_atomic_add v2, v3, v1, s[4:5] offset:16 sc0
	s_load_dword s101, s[4:5], 0x28
	s_waitcnt vmcnt(0)
	v_lshrrev_b32_e32 v2, s99, v2
	v_and_b32_e32 v2, 0xffff, v2
	v_add_u32_e32 v2, 1, v2
	s_lshl_b32 s98, s100, 5
	v_mov_b32_e32 v3, 0
	v_mov_b32_e32 v1, 1
	v_cmp_eq_u32_e32 vcc, s98, v2
	s_waitcnt lgkmcnt(0)
	s_lshr_b32 s101, s101, 5
	s_mul_i32 s99, s100, s101
	s_and_saveexec_b64 s[6:7], vcc
	s_cbranch_execz .Lhs_nl_5
	buffer_wbl2 sc1
	s_waitcnt vmcnt(0)
	global_atomic_add v3, v1, s[4:5] offset:36

; #define SEAM(k) do { if (IN(k) && IN((k) + 1)) grid.sync(); if (PROBE_PH >= 0) { const unsigned long long tn_ = __builtin_amdgcn_s_memrealtime(); if ((PROBE_PH >> (k)) & 1) tp1 += tn_ - tp0; tp0 = tn_; } } while (0)
; __global__ void __launch_bounds__(512, 2) mega(Params p) {
;     ...
;     SEAM(6);
.LBB0_658:
	v_readlane_b32 s2, v251, 32
	v_readlane_b32 s3, v251, 33
	s_waitcnt lgkmcnt(0)
	s_load_dwordx16 s[4:19], s[2:3], 0x110
	s_cmp_gt_i32 s67, 7
	s_cselect_b64 s[2:3], -1, 0
	s_and_b64 s[0:1], s[0:1], s[2:3]
	s_andn2_b64 vcc, exec, s[0:1]
	s_waitcnt lgkmcnt(0)
	v_writelane_b32 v250, s4, 5
	s_nop 1
	v_writelane_b32 v250, s5, 6
	v_writelane_b32 v250, s6, 7
	v_writelane_b32 v250, s7, 8
	v_writelane_b32 v250, s8, 9
	v_writelane_b32 v250, s9, 10
	v_writelane_b32 v250, s10, 11
	v_writelane_b32 v250, s11, 12
	v_writelane_b32 v250, s12, 13
	v_writelane_b32 v250, s13, 14
	v_writelane_b32 v250, s14, 15
	v_writelane_b32 v250, s15, 16
	v_writelane_b32 v250, s16, 17
	v_writelane_b32 v250, s17, 18
	v_writelane_b32 v250, s18, 19
	v_writelane_b32 v250, s19, 20
	s_cbranch_vccnz .LBB0_670
	v_and_b32_e32 v1, 0x3fffffff, v0
	v_cmp_eq_u32_e32 vcc, 0, v1
	s_waitcnt vmcnt(0)
	s_barrier
	s_and_saveexec_b64 s[0:1], vcc
	s_cbranch_execz .LBB0_669
	s_load_dwordx2 s[4:5], s[68:69], 0x58
	s_getreg_b32 s101, hwreg(HW_REG_XCC_ID)
	s_add_u32 s100, s100, 1
	s_and_b32 s101, s101, 7
	s_lshr_b32 s98, s101, 1
	s_lshl_b32 s98, s98, 2
	s_and_b32 s99, s101, 1
	s_lshl_b32 s99, s99, 4
	v_mov_b32_e32 v3, s98
	v_mov_b32_e32 v1, 1
	v_lshlrev_b32_e32 v1, s99, v1
	s_waitcnt vmcnt(0) lgkmcnt(0)
	global_atomic_add v2, v3, v1, s[4:5] offset:16 sc0
	s_load_dword s101, s[4:5], 0x28
	s_waitcnt vmcnt(0)
	v_lshrrev_b32_e32 v2, s99, v2
	v_and_b32_e32 v2, 0xffff, v2
	v_add_u32_e32 v2, 1, v2
	s_lshl_b32 s98, s100, 5
	v_mov_b32_e32 v3, 0
	v_mov_b32_e32 v1, 1
	v_cmp_eq_u32_e32 vcc, s98, v2
	s_waitcnt lgkmcnt(0)
	s_lshr_b32 s101, s101, 5
	s_mul_i32 s99, s100, s101
	s_and_saveexec_b64 s[6:7], vcc
	s_cbranch_execz .Lhs_nl_6
	buffer_wbl2 sc1
	s_waitcnt vmcnt(0)
	global_atomic_add v3, v1, s[4:5] offset:36

; #define SEAM(k) do { if (IN(k) && IN((k) + 1)) grid.sync(); if (PROBE_PH >= 0) { const unsigned long long tn_ = __builtin_amdgcn_s_memrealtime(); if ((PROBE_PH >> (k)) & 1) tp1 += tn_ - tp0; tp0 = tn_; } } while (0)
; __global__ void __launch_bounds__(512, 2) mega(Params p) {
;     ...
;     SEAM(7);
.LBB0_699:
	s_cmp_gt_i32 s67, 8
	s_cselect_b64 s[2:3], -1, 0
	s_and_b64 s[0:1], s[0:1], s[2:3]
	s_andn2_b64 vcc, exec, s[0:1]
	s_cbranch_vccnz .LBB0_711
	v_and_b32_e32 v1, 0x3fffffff, v0
	v_cmp_eq_u32_e32 vcc, 0, v1
	s_barrier
	s_and_saveexec_b64 s[0:1], vcc
	s_cbranch_execz .LBB0_710
	s_load_dwordx2 s[4:5], s[68:69], 0x58
	s_getreg_b32 s101, hwreg(HW_REG_XCC_ID)
	s_add_u32 s100, s100, 1
	s_and_b32 s101, s101, 7
	s_lshr_b32 s98, s101, 1
	s_lshl_b32 s98, s98, 2
	s_and_b32 s99, s101, 1
	s_lshl_b32 s99, s99, 4
	v_mov_b32_e32 v3, s98
	v_mov_b32_e32 v1, 1
	v_lshlrev_b32_e32 v1, s99, v1
	s_waitcnt vmcnt(0) lgkmcnt(0)
	global_atomic_add v2, v3, v1, s[4:5] offset:16 sc0
	s_load_dword s101, s[4:5], 0x28
	s_waitcnt vmcnt(0)
	v_lshrrev_b32_e32 v2, s99, v2
	v_and_b32_e32 v2, 0xffff, v2
	v_add_u32_e32 v2, 1, v2
	s_lshl_b32 s98, s100, 5
	v_mov_b32_e32 v3, 0
	v_mov_b32_e32 v1, 1
	v_cmp_eq_u32_e32 vcc, s98, v2
	s_waitcnt lgkmcnt(0)
	s_lshr_b32 s101, s101, 5
	s_mul_i32 s99, s100, s101
	s_and_saveexec_b64 s[6:7], vcc
	s_cbranch_execz .Lhs_nl_7
	buffer_wbl2 sc1
	s_waitcnt vmcnt(0)
	global_atomic_add v3, v1, s[4:5] offset:36

; #define SEAM(k) do { if (IN(k) && IN((k) + 1)) grid.sync(); if (PROBE_PH >= 0) { const unsigned long long tn_ = __builtin_amdgcn_s_memrealtime(); if ((PROBE_PH >> (k)) & 1) tp1 += tn_ - tp0; tp0 = tn_; } } while (0)
; __global__ void __launch_bounds__(512, 2) mega(Params p) {
;     ...
;     SEAM(8);
.LBB0_814:
	s_cmp_gt_i32 s67, 9
	s_cselect_b64 s[0:1], -1, 0
	s_and_b64 s[2:3], s[6:7], s[0:1]
	s_andn2_b64 vcc, exec, s[2:3]
	s_cbranch_vccnz .LBB0_826
	v_and_b32_e32 v1, 0x3fffffff, v0
	v_cmp_eq_u32_e32 vcc, 0, v1
	s_waitcnt vmcnt(0) lgkmcnt(0)
	s_barrier
	s_and_saveexec_b64 s[2:3], vcc
	s_cbranch_execz .LBB0_825
	s_load_dwordx2 s[4:5], s[68:69], 0x58
	s_getreg_b32 s101, hwreg(HW_REG_XCC_ID)
	s_add_u32 s100, s100, 1
	s_and_b32 s101, s101, 7
	s_lshr_b32 s98, s101, 1
	s_lshl_b32 s98, s98, 2
	s_and_b32 s99, s101, 1
	s_lshl_b32 s99, s99, 4
	v_mov_b32_e32 v3, s98
	v_mov_b32_e32 v1, 1
	v_lshlrev_b32_e32 v1, s99, v1
	s_waitcnt vmcnt(0) lgkmcnt(0)
	global_atomic_add v2, v3, v1, s[4:5] offset:16 sc0
	s_load_dword s101, s[4:5], 0x28
	s_waitcnt vmcnt(0)
	v_lshrrev_b32_e32 v2, s99, v2
	v_and_b32_e32 v2, 0xffff, v2
	v_add_u32_e32 v2, 1, v2
	s_lshl_b32 s98, s100, 5
	v_mov_b32_e32 v3, 0
	v_mov_b32_e32 v1, 1
	v_cmp_eq_u32_e32 vcc, s98, v2
	s_waitcnt lgkmcnt(0)
	s_lshr_b32 s101, s101, 5
	s_mul_i32 s99, s100, s101
	s_and_saveexec_b64 s[6:7], vcc
	s_cbranch_execz .Lhs_nl_8
	buffer_wbl2 sc1
	s_waitcnt vmcnt(0)
	global_atomic_add v3, v1, s[4:5] offset:36

; __global__ void __launch_bounds__(512, 2) mega(Params p) {
;     ...
;         grid.sync();
.LBB0_832:
	s_or_b64 exec, exec, s[0:1]
	v_lshrrev_b32_e32 v1, 20, v0
	v_lshrrev_b32_e32 v2, 10, v0
	v_or_b32_e32 v1, v2, v1
	s_movk_i32 s0, 0x3ff
	v_and_or_b32 v1, v1, s0, v103
	v_cmp_eq_u32_e32 vcc, 0, v1
	s_waitcnt lgkmcnt(0)
	s_barrier
	s_and_saveexec_b64 s[0:1], vcc
	s_cbranch_execz .LBB0_842
	s_load_dwordx2 s[2:3], s[68:69], 0x58
	s_getreg_b32 s101, hwreg(HW_REG_XCC_ID)
	s_add_u32 s100, s100, 1
	s_and_b32 s101, s101, 7
	s_lshr_b32 s98, s101, 1
	s_lshl_b32 s98, s98, 2
	s_and_b32 s99, s101, 1
	s_lshl_b32 s99, s99, 4
	v_mov_b32_e32 v3, s98
	v_mov_b32_e32 v1, 1
	v_lshlrev_b32_e32 v1, s99, v1
	s_waitcnt vmcnt(0) lgkmcnt(0)
	global_atomic_add v2, v3, v1, s[2:3] offset:16 sc0
	s_load_dword s101, s[2:3], 0x28
	s_waitcnt vmcnt(0)
	v_lshrrev_b32_e32 v2, s99, v2
	v_and_b32_e32 v2, 0xffff, v2
	v_add_u32_e32 v2, 1, v2
	s_lshl_b32 s98, s100, 5
	v_mov_b32_e32 v3, 0
	v_mov_b32_e32 v1, 1
	v_cmp_eq_u32_e32 vcc, s98, v2
	s_waitcnt lgkmcnt(0)
	s_lshr_b32 s101, s101, 5
	s_mul_i32 s99, s100, s101
	s_and_saveexec_b64 s[4:5], vcc
	s_cbranch_execz .Lhs_nl_9
	buffer_wbl2 sc1
	s_waitcnt vmcnt(0)
	global_atomic_add v3, v1, s[2:3] offset:36
.Lhs_nl_9:
	s_mov_b64 exec, s[4:5]
	s_mov_b64 s[4:5], 0
.Lhs_poll_9:
	global_load_dword v2, v3, s[2:3] offset:36 sc1
	s_waitcnt vmcnt(0)
	v_subrev_u32_e32 v2, s99, v2
	v_cmp_le_i32_e32 vcc, 0, v2
	s_or_b64 s[4:5], vcc, s[4:5]
	s_andn2_b64 exec, exec, s[4:5]
	s_cbranch_execz .Lhs_done_9
	s_sleep 2
	s_branch .Lhs_poll_9

; #define SEAM(k) do { if (IN(k) && IN((k) + 1)) grid.sync(); if (PROBE_PH >= 0) { const unsigned long long tn_ = __builtin_amdgcn_s_memrealtime(); if ((PROBE_PH >> (k)) & 1) tp1 += tn_ - tp0; tp0 = tn_; } } while (0)
; __global__ void __launch_bounds__(512, 2) mega(Params p) {
;     ...
;     SEAM(9);
.LBB0_1028:
	s_cmp_gt_i32 s67, 10
	v_readlane_b32 s2, v250, 45
	s_cselect_b64 s[0:1], -1, 0
	v_readlane_b32 s3, v250, 46
	s_and_b64 s[2:3], s[2:3], s[0:1]
	s_andn2_b64 vcc, exec, s[2:3]
	s_cbranch_vccnz .LBB0_1040
	v_and_b32_e32 v1, 0x3fffffff, v0
	v_cmp_eq_u32_e32 vcc, 0, v1
	s_waitcnt vmcnt(0) lgkmcnt(0)
	s_barrier
	s_and_saveexec_b64 s[2:3], vcc
	s_cbranch_execz .LBB0_1039
	s_load_dwordx2 s[4:5], s[68:69], 0x58
	s_getreg_b32 s101, hwreg(HW_REG_XCC_ID)
	s_add_u32 s100, s100, 1
	s_and_b32 s101, s101, 7
	s_lshr_b32 s98, s101, 1
	s_lshl_b32 s98, s98, 2
	s_and_b32 s99, s101, 1
	s_lshl_b32 s99, s99, 4
	v_mov_b32_e32 v3, s98
	v_mov_b32_e32 v1, 1
	v_lshlrev_b32_e32 v1, s99, v1
	s_waitcnt vmcnt(0) lgkmcnt(0)
	global_atomic_add v2, v3, v1, s[4:5] offset:16 sc0
	s_load_dword s101, s[4:5], 0x28
	s_waitcnt vmcnt(0)
	v_lshrrev_b32_e32 v2, s99, v2
	v_and_b32_e32 v2, 0xffff, v2
	v_add_u32_e32 v2, 1, v2
	s_lshl_b32 s98, s100, 5
	v_mov_b32_e32 v3, 0
	v_mov_b32_e32 v1, 1
	v_cmp_eq_u32_e32 vcc, s98, v2
	s_waitcnt lgkmcnt(0)
	s_lshr_b32 s101, s101, 5
	s_mul_i32 s99, s100, s101
	s_and_saveexec_b64 s[6:7], vcc
	s_cbranch_execz .Lhs_nl_10
	buffer_wbl2 sc1
	s_waitcnt vmcnt(0)
	global_atomic_add v3, v1, s[4:5] offset:36

; #define SEAM(k) do { if (IN(k) && IN((k) + 1)) grid.sync(); if (PROBE_PH >= 0) { const unsigned long long tn_ = __builtin_amdgcn_s_memrealtime(); if ((PROBE_PH >> (k)) & 1) tp1 += tn_ - tp0; tp0 = tn_; } } while (0)
; __global__ void __launch_bounds__(512, 2) mega(Params p) {
;     ...
;     SEAM(10);
.LBB0_1061:
	s_cmp_gt_i32 s67, 11
	s_cselect_b64 s[0:1], -1, 0
	s_and_b64 s[2:3], s[8:9], s[0:1]
	s_andn2_b64 vcc, exec, s[2:3]
	s_cbranch_vccnz .LBB0_1073
	v_and_b32_e32 v1, 0x3fffffff, v0
	v_cmp_eq_u32_e32 vcc, 0, v1
	s_waitcnt vmcnt(0) lgkmcnt(0)
	s_barrier
	s_and_saveexec_b64 s[2:3], vcc
	s_cbranch_execz .LBB0_1072
	s_load_dwordx2 s[4:5], s[68:69], 0x58
	s_getreg_b32 s101, hwreg(HW_REG_XCC_ID)
	s_add_u32 s100, s100, 1
	s_and_b32 s101, s101, 7
	s_lshr_b32 s98, s101, 1
	s_lshl_b32 s98, s98, 2
	s_and_b32 s99, s101, 1
	s_lshl_b32 s99, s99, 4
	v_mov_b32_e32 v3, s98
	v_mov_b32_e32 v1, 1
	v_lshlrev_b32_e32 v1, s99, v1
	s_waitcnt vmcnt(0) lgkmcnt(0)
	global_atomic_add v2, v3, v1, s[4:5] offset:16 sc0
	s_load_dword s101, s[4:5], 0x28
	s_waitcnt vmcnt(0)
	v_lshrrev_b32_e32 v2, s99, v2
	v_and_b32_e32 v2, 0xffff, v2
	v_add_u32_e32 v2, 1, v2
	s_lshl_b32 s98, s100, 5
	v_mov_b32_e32 v3, 0
	v_mov_b32_e32 v1, 1
	v_cmp_eq_u32_e32 vcc, s98, v2
	s_waitcnt lgkmcnt(0)
	s_lshr_b32 s101, s101, 5
	s_mul_i32 s99, s100, s101
	s_and_saveexec_b64 s[6:7], vcc
	s_cbranch_execz .Lhs_nl_11
	buffer_wbl2 sc1
	s_waitcnt vmcnt(0)
	global_atomic_add v3, v1, s[4:5] offset:36

; #define SEAM(k) do { if (IN(k) && IN((k) + 1)) grid.sync(); if (PROBE_PH >= 0) { const unsigned long long tn_ = __builtin_amdgcn_s_memrealtime(); if ((PROBE_PH >> (k)) & 1) tp1 += tn_ - tp0; tp0 = tn_; } } while (0)
; __global__ void __launch_bounds__(512, 2) mega(Params p) {
;     ...
;     SEAM(11);
.LBB0_1094:
	s_cmp_gt_i32 s67, 12
	s_cselect_b64 s[0:1], -1, 0
	s_and_b64 s[2:3], s[2:3], s[0:1]
	s_andn2_b64 vcc, exec, s[2:3]
	s_cbranch_vccnz .LBB0_1106
	v_and_b32_e32 v1, 0x3fffffff, v0
	v_cmp_eq_u32_e32 vcc, 0, v1
	s_waitcnt vmcnt(0) lgkmcnt(0)
	s_barrier
	s_and_saveexec_b64 s[2:3], vcc
	s_cbranch_execz .LBB0_1105
	s_load_dwordx2 s[4:5], s[68:69], 0x58
	s_getreg_b32 s101, hwreg(HW_REG_XCC_ID)
	s_add_u32 s100, s100, 1
	s_and_b32 s101, s101, 7
	s_lshr_b32 s98, s101, 1
	s_lshl_b32 s98, s98, 2
	s_and_b32 s99, s101, 1
	s_lshl_b32 s99, s99, 4
	v_mov_b32_e32 v3, s98
	v_mov_b32_e32 v1, 1
	v_lshlrev_b32_e32 v1, s99, v1
	s_waitcnt vmcnt(0) lgkmcnt(0)
	global_atomic_add v2, v3, v1, s[4:5] offset:16 sc0
	s_load_dword s101, s[4:5], 0x28
	s_waitcnt vmcnt(0)
	v_lshrrev_b32_e32 v2, s99, v2
	v_and_b32_e32 v2, 0xffff, v2
	v_add_u32_e32 v2, 1, v2
	s_lshl_b32 s98, s100, 5
	v_mov_b32_e32 v3, 0
	v_mov_b32_e32 v1, 1
	v_cmp_eq_u32_e32 vcc, s98, v2
	s_waitcnt lgkmcnt(0)
	s_lshr_b32 s101, s101, 5
	s_mul_i32 s99, s100, s101
	s_and_saveexec_b64 s[6:7], vcc
	s_cbranch_execz .Lhs_nl_12
	buffer_wbl2 sc1
	s_waitcnt vmcnt(0)
	global_atomic_add v3, v1, s[4:5] offset:36
